# diff: K/V^T tiles fetched HBM->LDS directly too (tile it+2 at iteration start), on top of the MLA LDS-DMA staging
# speedup vs baseline: 1.0116x; 1.0020x over previous
; #define LAS __attribute__((address_space(3)))
; template <int DQK, int DV, int FLAGS, int qp, int kp, int vts, int op> ...
;     ...
;     u32x4 kreg[KPT], vreg[VPT];
;     unsigned kgo[KPT], vgo[VPT], klo[KPT], vlo[VPT];
; #pragma unroll
;     for (int i = 0; i < KPT; ++i) { const int c = tid + i * NTHREADS; const int row = c / KC, cc = c % KC; kgo[i] = (unsigned)(row * kp + cc * 8) * 2u; klo[i] = (unsigned)(row * KROW + cc * 16); }
; #pragma unroll
;     for (int i = 0; i < VPT; ++i) { const int c = tid + i * NTHREADS; const int d = c >> 3, cc = c & 7; vgo[i] = (unsigned)(d * vts + cc * 8) * 2u; vlo[i] = (unsigned)(KT_BYTES + d * VROW + cc * 16); }
;     ...
;     ATT_GLOAD((FLAGS & AF_REV) ? kt_hi - 1 : kt_lo); ATT_LSTORE(0);
;     __syncthreads();
;     bool started = false;
;     const int prow = (r32 & ~12) | ((r32 & 4) << 1) | ((r32 & 8) >> 1);
;     const int ntile = kt_hi - kt_lo;
;     ...
;             for (int i = 0; i < 2; ++i) { kf[0][2 * i] = *(const LAS bf16x8*)(kb + i * 32); kf[0][2 * i + 1] = *(const LAS bf16x8*)(kb + 32 * KROW + i * 32); }
;             const int nrel = qpos - kv0 - 8 * hi;
;             if (FLAGS & AF_ALIBI) { const float ab = -slope2 * (float)nrel - ((FLAGS & AF_ROBUST) ? 0.f : m);
; #pragma unroll
;                 for (int r = 0; r < 16; ++r) { const float c = (float)(16 * (r >> 3) + (r & 7)); p0[r] = __builtin_fmaf(slope2, c, ab); p1[r] = __builtin_fmaf(slope2, c + 32.f, ab); }
;             } else if (FLAGS & AF_ROBUST) {
; #pragma unroll
;                 for (int r = 0; r < 16; ++r) { p0[r] = 0.f; p1[r] = 0.f; }
;             } else { p0 = negm; p1 = negm; }
;             __builtin_amdgcn_sched_barrier(0);
; #pragma unroll
;             for (int c = 0; c < ND0 / 2; ++c) {
;                 if (c + 1 < ND0 / 2) {
; #pragma unroll
;                     for (int i = 0; i < 2; ++i) { kf[(c + 1) & 1][2 * i] = *(const LAS bf16x8*)(kb + (2 * c + 2 + i) * 32); kf[(c + 1) & 1][2 * i + 1] = *(const LAS bf16x8*)(kb + 32 * KROW + (2 * c + 2 + i) * 32); }
;                 }
; #pragma unroll
;                 for (int i = 0; i < 2; ++i) {
;                     p0 = __builtin_amdgcn_mfma_f32_32x32x16_bf16(kf[c & 1][2 * i], qr[2 * c + i], p0, 0, 0, 0);
;                     p1 = __builtin_amdgcn_mfma_f32_32x32x16_bf16(kf[c & 1][2 * i + 1], qr[2 * c + i], p1, 0, 0, 0);
;                 }
.LBB0_933:
	s_andn2_b64 vcc, exec, s[8:9]
	v_lshlrev_b32_e32 v198, 3, v17
	s_cbranch_vccnz .LBB0_923
	v_and_b32_e32 v18, 31, v15
	v_and_b32_e32 v19, 19, v15
	v_lshlrev_b32_e32 v20, 1, v15
	v_lshrrev_b32_e32 v15, 1, v15
	s_and_b32 s8, s2, 0xffffffe0
	v_readlane_b32 s12, v255, 39
	v_and_b32_e32 v20, 8, v20
	v_and_b32_e32 v15, 4, v15
	v_mov_b32_e32 v17, v1
	s_add_i32 s20, s8, s12
	v_or3_b32 v15, v19, v20, v15
	s_addk_i32 s8, 0xff40
	v_mov_b32_e32 v64, v1
	v_mov_b32_e32 v65, v1
	v_mul_u32_u24_e32 v201, 0x90, v15
	v_mul_u32_u24_e32 v203, 0x90, v18
	v_lshl_add_u64 v[206:207], s[6:7], 0, v[16:17]
	v_add_u32_e32 v15, s8, v18
	v_mov_b32_e32 v66, v1
	v_mov_b32_e32 v67, v1
	v_mov_b32_e32 v68, v1
	v_mov_b32_e32 v69, v1
	v_mov_b32_e32 v70, v1
	v_mov_b32_e32 v71, v1
	v_mov_b32_e32 v72, v1
	v_mov_b32_e32 v73, v1
	v_mov_b32_e32 v74, v1
	v_mov_b32_e32 v75, v1
	v_mov_b32_e32 v76, v1
	v_mov_b32_e32 v77, v1
	v_mov_b32_e32 v78, v1
	v_mov_b32_e32 v79, v1
	v_mov_b64_e32 v[48:49], v[64:65]
	v_mov_b64_e32 v[32:33], v[64:65]
	v_mov_b64_e32 v[16:17], v[64:65]
	v_mov_b32_e32 v197, v1
	s_or_b32 s21, s20, 31
	s_add_i32 s2, s3, 0xff
	s_addk_i32 s3, 0x100
	v_mov_b32_e32 v208, v14
	v_mov_b32_e32 v209, v14
	v_mov_b32_e32 v210, v14
	v_mov_b32_e32 v211, v14
	s_sub_i32 s34, 0xfe, s11
	v_sub_u32_e32 v205, v15, v198
	s_sub_i32 s22, 0x3fff, s10
	s_mov_b32 s23, 0
	s_mov_b64 s[36:37], 0
	v_mov_b32_e32 v222, 0
	v_mov_b64_e32 v[50:51], v[66:67]
	v_mov_b64_e32 v[52:53], v[68:69]
	v_mov_b64_e32 v[54:55], v[70:71]
	v_mov_b64_e32 v[56:57], v[72:73]
	v_mov_b64_e32 v[58:59], v[74:75]
	v_mov_b64_e32 v[60:61], v[76:77]
	v_mov_b64_e32 v[62:63], v[78:79]
	v_mov_b64_e32 v[34:35], v[66:67]
	v_mov_b64_e32 v[36:37], v[68:69]
	v_mov_b64_e32 v[38:39], v[70:71]
	v_mov_b64_e32 v[40:41], v[72:73]
	v_mov_b64_e32 v[42:43], v[74:75]
	v_mov_b64_e32 v[44:45], v[76:77]
	v_mov_b64_e32 v[46:47], v[78:79]
	v_mov_b64_e32 v[18:19], v[66:67]
	v_mov_b64_e32 v[20:21], v[68:69]
	v_mov_b64_e32 v[22:23], v[70:71]
	v_mov_b64_e32 v[24:25], v[72:73]
	v_mov_b64_e32 v[26:27], v[74:75]
	v_mov_b64_e32 v[28:29], v[76:77]
	v_mov_b64_e32 v[30:31], v[78:79]
	v_mov_b32_e32 v199, 0
	v_readlane_b32 s13, v255, 40
	s_andn2_b64 vcc, exec, s[40:41]
	s_cbranch_vccnz .Ld_fallback
	v_readfirstlane_b32 s12, v212
	s_lshr_b32 s12, s12, 6
	s_lshl_b32 s98, s12, 10
	s_lshl_b32 s13, s12, 14
	v_readfirstlane_b32 s100, v206
	v_readfirstlane_b32 s101, v207
	s_sub_u32 s100, s100, s13
	s_subb_u32 s101, s101, 0
	v_and_b32_e32 v240, 63, v212
	s_add_i32 s13, s12, 0
	v_lshl_add_u32 v241, s13, 6, v240
	s_cmp_ge_u32 s13, 9
	s_movk_i32 m0, 0x800
	s_cselect_b32 m0, 0x8000, m0
	s_cselect_b32 s13, 576, 0
	s_nop 3
	v_subrev_u32_e32 v241, s13, v241
	v_mul_u32_u24_e32 v246, 7282, v241
	v_lshrrev_b32_e32 v246, 16, v246
	v_mul_u32_u24_e32 v247, 9, v246
	v_sub_u32_e32 v247, v241, v247
	v_min_u32_e32 v247, 7, v247
	v_mul_u32_u24_e32 v246, m0, v246
	v_lshl_add_u32 v148, v247, 4, v246
	s_add_i32 s13, s12, 8
	v_lshl_add_u32 v241, s13, 6, v240
	s_cmp_ge_u32 s13, 9
	s_movk_i32 m0, 0x800
	s_cselect_b32 m0, 0x8000, m0
	s_cselect_b32 s13, 576, 0
	s_nop 3
	v_subrev_u32_e32 v241, s13, v241
	v_mul_u32_u24_e32 v246, 7282, v241
	v_lshrrev_b32_e32 v246, 16, v246
	v_mul_u32_u24_e32 v247, 9, v246
	v_sub_u32_e32 v247, v241, v247
	v_min_u32_e32 v247, 7, v247
	v_mul_u32_u24_e32 v246, m0, v246
	v_lshl_add_u32 v149, v247, 4, v246
	s_add_i32 s13, s12, 16
	v_lshl_add_u32 v241, s13, 6, v240
	s_cmp_ge_u32 s13, 9
	s_movk_i32 m0, 0x800
	s_cselect_b32 m0, 0x8000, m0
	s_cselect_b32 s13, 576, 0
	s_nop 3
	v_subrev_u32_e32 v241, s13, v241
	v_mul_u32_u24_e32 v246, 7282, v241
	v_lshrrev_b32_e32 v246, 16, v246
	v_mul_u32_u24_e32 v247, 9, v246
	v_sub_u32_e32 v247, v241, v247
	v_min_u32_e32 v247, 7, v247
	v_mul_u32_u24_e32 v246, m0, v246
	v_lshl_add_u32 v150, v247, 4, v246
	s_add_i32 s13, s12, 24
	v_lshl_add_u32 v241, s13, 6, v240
	s_cmp_ge_u32 s13, 9
	s_movk_i32 m0, 0x800
	s_cselect_b32 m0, 0x8000, m0
	s_cselect_b32 s13, 576, 0
	s_nop 3
	v_subrev_u32_e32 v241, s13, v241
	v_mul_u32_u24_e32 v246, 7282, v241
	v_lshrrev_b32_e32 v246, 16, v246
	v_mul_u32_u24_e32 v247, 9, v246
	v_sub_u32_e32 v247, v241, v247
	v_min_u32_e32 v247, 7, v247
	v_mul_u32_u24_e32 v246, m0, v246
	v_lshl_add_u32 v151, v247, 4, v246
	v_add_u32_e32 v244, v201, v194
	v_add_u32_e32 v245, 0xd800, v244
	v_add_u32_e32 v251, v203, v194
	v_add_u32_e32 v250, 0xd800, v251
	s_add_i32 s34, s34, -1
	s_waitcnt vmcnt(0)
	ds_write_b128 v204, v[224:227] offset:27648
	ds_write_b128 v200, v[228:231] offset:36864
	ds_write_b128 v200, v[232:235] offset:46080
	s_mov_b32 s8, 0x42000000
	s_mov_b32 s9, 0x42040000
	s_sub_i32 s24, s22, s21
	s_ashr_i32 s24, s24, 6
	s_max_i32 s24, s24, 0
	s_waitcnt lgkmcnt(0)
	s_barrier
	s_cmp_lg_u32 s24, 0
	s_cbranch_scc1 .Ld_noqk0
	ds_read_b128 v[160:163], v244 offset:0
	ds_read_b128 v[164:167], v244 offset:32
	ds_read_b128 v[168:171], v244 offset:64
	ds_read_b128 v[172:175], v244 offset:96
	ds_read_b128 v[224:227], v244 offset:4608
	ds_read_b128 v[228:231], v244 offset:4640
	ds_read_b128 v[232:235], v244 offset:4672
	ds_read_b128 v[236:239], v244 offset:4704
	v_cvt_f32_i32_e32 v246, v205
	v_fma_f32 v242, -v14, v246, -v222
	v_mov_b32_e32 v80, v242
	v_add_f32_e32 v81, v14, v242
	v_fma_f32 v82, v14, s62, v242
	v_fma_f32 v83, v14, s63, v242
	v_fma_f32 v84, v14, s64, v242
	v_fma_f32 v85, v14, s65, v242
	v_fma_f32 v86, v14, s66, v242
	v_fma_f32 v87, v14, s67, v242
	v_fma_f32 v88, v14, s68, v242
	v_fma_f32 v89, v14, s69, v242
	v_fma_f32 v90, v14, s70, v242
	v_fma_f32 v91, v14, s71, v242
	v_fma_f32 v92, v14, s72, v242
	v_fma_f32 v93, v14, s73, v242
	v_fma_f32 v94, v14, s76, v242
	v_fma_f32 v95, v14, s77, v242
	v_fma_f32 v96, v14, s8, v242
	v_fma_f32 v97, v14, s9, v242
	v_fma_f32 v98, v14, s96, v242
	v_fma_f32 v99, v14, s97, v242
	v_fma_f32 v100, v14, s94, v242
	v_fma_f32 v101, v14, s95, v242
	v_fma_f32 v102, v14, s92, v242
	v_fma_f32 v103, v14, s93, v242
	v_fma_f32 v104, v14, s90, v242
	v_fma_f32 v105, v14, s91, v242
	v_fma_f32 v106, v14, s88, v242
	v_fma_f32 v107, v14, s89, v242
	v_fma_f32 v108, v14, s86, v242
	v_fma_f32 v109, v14, s87, v242
	v_fma_f32 v110, v14, s78, v242
	v_fma_f32 v111, v14, s79, v242
	s_waitcnt lgkmcnt(0)
	v_mfma_f32_32x32x16_bf16 v[80:95], v[160:163], v[2:5], v[80:95]
	v_mfma_f32_32x32x16_bf16 v[96:111], v[224:227], v[2:5], v[96:111]
	v_mfma_f32_32x32x16_bf16 v[80:95], v[164:167], v[6:9], v[80:95]
	v_mfma_f32_32x32x16_bf16 v[96:111], v[228:231], v[6:9], v[96:111]
	v_mfma_f32_32x32x16_bf16 v[80:95], v[168:171], v[10:13], v[80:95]
	v_mfma_f32_32x32x16_bf16 v[96:111], v[232:235], v[10:13], v[96:111]
	v_mfma_f32_32x32x16_bf16 v[80:95], v[172:175], v[144:147], v[80:95]
	v_mfma_f32_32x32x16_bf16 v[96:111], v[236:239], v[144:147], v[96:111]
; template <int DQK, int DV, int FLAGS, int qp, int kp, int vts, int op> ...
;     ...
;             if (more) ATT_GLOAD((FLAGS & AF_REV) ? t - 1 : t + 1);
.Ld_noqk0:
.Ld_top0:
	s_cmp_le_i32 s23, s24
	s_cbranch_scc1 .Ld_gen0
	s_add_i32 s13, s23, 1
	s_cmp_ge_i32 s13, s3
	s_cbranch_scc1 .Ld_gen0
	ds_read_b128 v[224:227], v250 offset:41472
	ds_read_b128 v[228:231], v250 offset:41504
	ds_read_b128 v[232:235], v250 offset:41536
	ds_read_b128 v[236:239], v250 offset:41568
	v_mfma_f32_32x32x16_bf16 v[64:79], v[160:163], v[112:115], v[64:79]
	v_exp_f32_e32 v80, v80
	v_exp_f32_e32 v81, v81
	v_exp_f32_e32 v96, v96
	v_exp_f32_e32 v97, v97
	v_add_u32_e32 v246, 64, v205
	s_add_i32 s12, s23, 2
	s_cmp_ge_i32 s12, s3
	s_cbranch_scc1 .Ld_ng_s0
	s_ashr_i32 s35, s34, 31
	s_lshl_b64 s[6:7], s[34:35], 17
	s_add_u32 s6, s6, s100
	s_addc_u32 s7, s7, s101
	s_lshl_b64 s[10:11], s[34:35], 7
	s_add_u32 s10, s18, s10
	s_addc_u32 s11, s19, s11
	s_add_i32 m0, s98, 0xd800
	s_nop 0
	global_load_lds_dwordx4 v148, s[6:7]
	s_cmp_eq_u32 s98, 0
	s_cselect_b64 s[12:13], s[6:7], s[10:11]
	s_add_i32 m0, s98, 0xf800
	s_nop 0
	global_load_lds_dwordx4 v149, s[12:13]
	s_add_i32 m0, s98, 0x11800
	s_nop 0
	global_load_lds_dwordx4 v150, s[10:11]
	s_cmp_lt_u32 s98, 0xc00
	s_cbranch_scc0 .Ld_no4_s0
	s_add_i32 m0, s98, 0x13800
	s_nop 0
	global_load_lds_dwordx4 v151, s[10:11]
.Ld_no4_s0:
	s_add_i32 s34, s34, -1
.Ld_ng_s0:
	v_mfma_f32_32x32x16_bf16 v[64:79], v[164:167], v[116:119], v[64:79]
	v_add_f32_e32 v240, v80, v199
	v_exp_f32_e32 v82, v82
	v_exp_f32_e32 v83, v83
	v_add_f32_e32 v240, v96, v240
	v_cvt_f32_i32_e32 v246, v246
	v_mfma_f32_32x32x16_bf16 v[64:79], v[168:171], v[120:123], v[64:79]
	v_add_f32_e32 v241, v81, v97
	v_exp_f32_e32 v98, v98
	v_exp_f32_e32 v99, v99
	v_add_f32_e32 v240, v82, v240
	v_fma_f32 v242, -v14, v246, -v222
	v_mfma_f32_32x32x16_bf16 v[64:79], v[172:175], v[124:127], v[64:79]
	v_add_f32_e32 v241, v83, v241
	v_exp_f32_e32 v84, v84
	v_exp_f32_e32 v85, v85
	v_add_f32_e32 v240, v98, v240
	v_fma_f32 v128, v14, s8, v242
	ds_read_b128 v[160:163], v250 offset:46080
	ds_read_b128 v[164:167], v250 offset:46112
	ds_read_b128 v[168:171], v250 offset:46144
	ds_read_b128 v[172:175], v250 offset:46176
	s_waitcnt lgkmcnt(4)
	v_mfma_f32_32x32x16_bf16 v[48:63], v[224:227], v[112:115], v[48:63]
	v_add_f32_e32 v241, v99, v241
	v_exp_f32_e32 v100, v100
	v_exp_f32_e32 v101, v101
	v_add_f32_e32 v240, v84, v240
	v_fma_f32 v129, v14, s9, v242
	v_mfma_f32_32x32x16_bf16 v[48:63], v[228:231], v[116:119], v[48:63]
	v_add_f32_e32 v241, v85, v241
	v_exp_f32_e32 v86, v86
	v_exp_f32_e32 v87, v87
	v_add_f32_e32 v240, v100, v240
	v_fma_f32 v130, v14, s96, v242
	v_mfma_f32_32x32x16_bf16 v[48:63], v[232:235], v[120:123], v[48:63]
	v_add_f32_e32 v241, v101, v241
	v_exp_f32_e32 v102, v102
	v_exp_f32_e32 v103, v103
	v_add_f32_e32 v240, v86, v240
	v_fma_f32 v131, v14, s97, v242
	v_mfma_f32_32x32x16_bf16 v[48:63], v[236:239], v[124:127], v[48:63]
	v_add_f32_e32 v241, v87, v241
	v_exp_f32_e32 v88, v88
	v_exp_f32_e32 v89, v89
	v_add_f32_e32 v240, v102, v240
	v_fma_f32 v132, v14, s94, v242
	ds_read_b128 v[224:227], v250 offset:50688
	ds_read_b128 v[228:231], v250 offset:50720
	ds_read_b128 v[232:235], v250 offset:50752
	ds_read_b128 v[236:239], v250 offset:50784
	s_waitcnt lgkmcnt(4)
	v_mfma_f32_32x32x16_bf16 v[32:47], v[160:163], v[112:115], v[32:47]
	v_add_f32_e32 v241, v103, v241
	v_exp_f32_e32 v104, v104
	v_exp_f32_e32 v105, v105
	v_add_f32_e32 v240, v88, v240
	v_fma_f32 v133, v14, s95, v242
	v_mfma_f32_32x32x16_bf16 v[32:47], v[164:167], v[116:119], v[32:47]
	v_add_f32_e32 v241, v89, v241
	v_exp_f32_e32 v90, v90
	v_exp_f32_e32 v91, v91
	v_add_f32_e32 v240, v104, v240
	v_fma_f32 v134, v14, s92, v242
	v_mfma_f32_32x32x16_bf16 v[32:47], v[168:171], v[120:123], v[32:47]
	v_add_f32_e32 v241, v105, v241
	v_exp_f32_e32 v106, v106
	v_exp_f32_e32 v107, v107
	v_add_f32_e32 v240, v90, v240
	v_fma_f32 v135, v14, s93, v242
	v_mfma_f32_32x32x16_bf16 v[32:47], v[172:175], v[124:127], v[32:47]
	v_add_f32_e32 v241, v91, v241
	v_exp_f32_e32 v92, v92
	v_exp_f32_e32 v93, v93
	v_add_f32_e32 v240, v106, v240
	v_fma_f32 v136, v14, s90, v242
	ds_read_b128 v[160:163], v244 offset:32256
	ds_read_b128 v[164:167], v244 offset:32288
	ds_read_b128 v[168:171], v244 offset:32320
	ds_read_b128 v[172:175], v244 offset:32352
	s_waitcnt lgkmcnt(4)
	v_mfma_f32_32x32x16_bf16 v[16:31], v[224:227], v[112:115], v[16:31]
	v_add_f32_e32 v241, v107, v241
	v_exp_f32_e32 v108, v108
	v_exp_f32_e32 v109, v109
	v_add_f32_e32 v240, v92, v240
	v_fma_f32 v137, v14, s91, v242
	v_mfma_f32_32x32x16_bf16 v[16:31], v[228:231], v[116:119], v[16:31]
	v_add_f32_e32 v241, v93, v241
	v_exp_f32_e32 v94, v94
	v_exp_f32_e32 v95, v95
	v_add_f32_e32 v240, v108, v240
	v_fma_f32 v138, v14, s88, v242
	v_mfma_f32_32x32x16_bf16 v[16:31], v[232:235], v[120:123], v[16:31]
	v_add_f32_e32 v241, v109, v241
	v_exp_f32_e32 v110, v110
	v_exp_f32_e32 v111, v111
	v_add_f32_e32 v240, v94, v240
	v_fma_f32 v139, v14, s89, v242
	v_mfma_f32_32x32x16_bf16 v[16:31], v[236:239], v[124:127], v[16:31]
	v_add_f32_e32 v241, v95, v241
	v_fma_f32 v140, v14, s86, v242
	v_fma_f32 v141, v14, s87, v242
	v_fma_f32 v142, v14, s78, v242
	v_fma_f32 v143, v14, s79, v242
	ds_read_b128 v[224:227], v244 offset:27648
	ds_read_b128 v[228:231], v244 offset:27680
	ds_read_b128 v[232:235], v244 offset:27712
	ds_read_b128 v[236:239], v244 offset:27744
	s_waitcnt lgkmcnt(4)
	v_mfma_f32_32x32x16_bf16 v[128:143], v[160:163], v[2:5], v[128:143]
	v_mov_b32_e32 v112, v242
	v_add_f32_e32 v113, v14, v242
	v_fma_f32 v114, v14, s62, v242
	v_fma_f32 v115, v14, s63, v242
	v_mfma_f32_32x32x16_bf16 v[128:143], v[164:167], v[6:9], v[128:143]
	v_fma_f32 v116, v14, s64, v242
	v_fma_f32 v117, v14, s65, v242
	v_fma_f32 v118, v14, s66, v242
	v_fma_f32 v119, v14, s67, v242
	v_mfma_f32_32x32x16_bf16 v[128:143], v[168:171], v[10:13], v[128:143]
	v_fma_f32 v120, v14, s68, v242
	v_fma_f32 v121, v14, s69, v242
	v_fma_f32 v122, v14, s70, v242
	v_fma_f32 v123, v14, s71, v242
	v_mfma_f32_32x32x16_bf16 v[128:143], v[172:175], v[144:147], v[128:143]
	v_fma_f32 v124, v14, s72, v242
	v_fma_f32 v125, v14, s73, v242
	v_fma_f32 v126, v14, s76, v242
	v_fma_f32 v127, v14, s77, v242
	ds_read_b128 v[160:163], v251 offset:9216
	ds_read_b128 v[164:167], v251 offset:9248
	ds_read_b128 v[168:171], v251 offset:9280
	ds_read_b128 v[172:175], v251 offset:9312
	s_waitcnt lgkmcnt(4)
	v_mfma_f32_32x32x16_bf16 v[112:127], v[224:227], v[2:5], v[112:127]
	s_nop 0
	v_add_f32_e32 v240, v110, v240
	v_add_f32_e32 v241, v111, v241
	v_cvt_pk_bf16_f32 v80, v80, v81
	v_cvt_pk_bf16_f32 v81, v82, v83
	v_cvt_pk_bf16_f32 v82, v84, v85
	v_mfma_f32_32x32x16_bf16 v[112:127], v[228:231], v[6:9], v[112:127]
	v_cvt_pk_bf16_f32 v83, v86, v87
	v_cvt_pk_bf16_f32 v84, v88, v89
	v_cvt_pk_bf16_f32 v85, v90, v91
	v_cvt_pk_bf16_f32 v86, v92, v93
	v_cvt_pk_bf16_f32 v87, v94, v95
	v_cvt_pk_bf16_f32 v88, v96, v97
	v_mfma_f32_32x32x16_bf16 v[112:127], v[232:235], v[10:13], v[112:127]
	v_cvt_pk_bf16_f32 v89, v98, v99
	v_cvt_pk_bf16_f32 v90, v100, v101
	v_cvt_pk_bf16_f32 v91, v102, v103
	v_cvt_pk_bf16_f32 v92, v104, v105
	v_cvt_pk_bf16_f32 v93, v106, v107
	v_cvt_pk_bf16_f32 v94, v108, v109
	v_mfma_f32_32x32x16_bf16 v[112:127], v[236:239], v[144:147], v[112:127]
	v_cvt_pk_bf16_f32 v95, v110, v111
	v_add_f32_e32 v199, v240, v241
	s_branch .Ld_tail0
.Ld_gen0:
	s_add_i32 s12, s23, 2
	s_cmp_ge_i32 s12, s3
	s_cbranch_scc1 .Ld_nols_q0
	s_and_b32 s99, s12, 3
	s_mulk_i32 s99, 0x6c00
	s_ashr_i32 s35, s34, 31
	s_lshl_b64 s[6:7], s[34:35], 17
	s_add_u32 s6, s6, s100
	s_addc_u32 s7, s7, s101
	s_lshl_b64 s[10:11], s[34:35], 7
	s_add_u32 s10, s18, s10
	s_addc_u32 s11, s19, s11
	s_add_i32 m0, s98, s99
	s_nop 0
	global_load_lds_dwordx4 v148, s[6:7]
	s_cmp_eq_u32 s98, 0
	s_cselect_b64 s[12:13], s[6:7], s[10:11]
	s_add_i32 m0, s98, s99
	s_add_i32 m0, m0, 0x2000
	s_nop 0
	global_load_lds_dwordx4 v149, s[12:13]
	s_add_i32 m0, s98, s99
	s_add_i32 m0, m0, 0x4000
	s_nop 0
	global_load_lds_dwordx4 v150, s[10:11]
	s_cmp_lt_u32 s98, 0xc00
	s_cbranch_scc0 .Ld_no4_gq0
	s_add_i32 m0, s98, s99
	s_add_i32 m0, m0, 0x6000
	s_nop 0
	global_load_lds_dwordx4 v151, s[10:11]

; #define ATT_LSTORE(buf) do { LAS unsigned char* b_ = lds + (buf) * BUF; \
;         _Pragma("unroll") for (int i = 0; i < KPT; ++i) { if (KCH % NTHREADS == 0 || tid + i * NTHREADS < KCH) *(LAS u32x4*)(b_ + klo[i]) = kreg[i]; } \
;         _Pragma("unroll") for (int i = 0; i < VPT; ++i) *(LAS u32x4*)(b_ + vlo[i]) = vreg[i]; } while (0)
; template <int DQK, int DV, int FLAGS, int qp, int kp, int vts, int op> ...
;     ...
;             if (more) ATT_GLOAD((FLAGS & AF_REV) ? t - 1 : t + 1);
;     ...
;         if (more) ATT_LSTORE(cur ^ 1);
;         __syncthreads();
.Ld_nopre_q0:
.Ld_tail0:
	s_waitcnt vmcnt(0)
	v_add_u32_e32 v205, 64, v205
	s_add_i32 s23, s23, 1
	s_cmp_ge_i32 s23, s3
	s_cbranch_scc1 .Ld_flush1
	s_waitcnt lgkmcnt(0)
	s_barrier
.Ld_top1:
	s_cmp_le_i32 s23, s24
	s_cbranch_scc1 .Ld_gen1
	s_add_i32 s13, s23, 1
	s_cmp_ge_i32 s13, s3
	s_cbranch_scc1 .Ld_gen1
	ds_read_b128 v[224:227], v251 offset:13824
	ds_read_b128 v[228:231], v251 offset:13856
	ds_read_b128 v[232:235], v251 offset:13888
	ds_read_b128 v[236:239], v251 offset:13920
	v_mfma_f32_32x32x16_bf16 v[64:79], v[160:163], v[80:83], v[64:79]
	v_exp_f32_e32 v112, v112
	v_exp_f32_e32 v113, v113
	v_exp_f32_e32 v128, v128
	v_exp_f32_e32 v129, v129
	v_add_u32_e32 v246, 64, v205
	s_add_i32 s12, s23, 2
	s_cmp_ge_i32 s12, s3
	s_cbranch_scc1 .Ld_ng_s1
	s_ashr_i32 s35, s34, 31
	s_lshl_b64 s[6:7], s[34:35], 17
	s_add_u32 s6, s6, s100
	s_addc_u32 s7, s7, s101
	s_lshl_b64 s[10:11], s[34:35], 7
	s_add_u32 s10, s18, s10
	s_addc_u32 s11, s19, s11
	s_add_i32 m0, s98, 0x14400
	s_nop 0
	global_load_lds_dwordx4 v148, s[6:7]
	s_cmp_eq_u32 s98, 0
	s_cselect_b64 s[12:13], s[6:7], s[10:11]
	s_add_i32 m0, s98, 0x16400
	s_nop 0
	global_load_lds_dwordx4 v149, s[12:13]
	s_add_i32 m0, s98, 0x18400
	s_nop 0
	global_load_lds_dwordx4 v150, s[10:11]
	s_cmp_lt_u32 s98, 0xc00
	s_cbranch_scc0 .Ld_no4_s1
	s_add_i32 m0, s98, 0x1a400
	s_nop 0
	global_load_lds_dwordx4 v151, s[10:11]

.Ld_ng_s1:
	v_mfma_f32_32x32x16_bf16 v[64:79], v[164:167], v[84:87], v[64:79]
	v_add_f32_e32 v240, v112, v199
	v_exp_f32_e32 v114, v114
	v_exp_f32_e32 v115, v115
	v_add_f32_e32 v240, v128, v240
	v_cvt_f32_i32_e32 v246, v246
	v_mfma_f32_32x32x16_bf16 v[64:79], v[168:171], v[88:91], v[64:79]
	v_add_f32_e32 v241, v113, v129
	v_exp_f32_e32 v130, v130
	v_exp_f32_e32 v131, v131
	v_add_f32_e32 v240, v114, v240
	v_fma_f32 v242, -v14, v246, -v222
	v_mfma_f32_32x32x16_bf16 v[64:79], v[172:175], v[92:95], v[64:79]
	v_add_f32_e32 v241, v115, v241
	v_exp_f32_e32 v116, v116
	v_exp_f32_e32 v117, v117
	v_add_f32_e32 v240, v130, v240
	v_fma_f32 v96, v14, s8, v242
	ds_read_b128 v[160:163], v251 offset:18432
	ds_read_b128 v[164:167], v251 offset:18464
	ds_read_b128 v[168:171], v251 offset:18496
	ds_read_b128 v[172:175], v251 offset:18528
	s_waitcnt lgkmcnt(4)
	v_mfma_f32_32x32x16_bf16 v[48:63], v[224:227], v[80:83], v[48:63]
	v_add_f32_e32 v241, v131, v241
	v_exp_f32_e32 v132, v132
	v_exp_f32_e32 v133, v133
	v_add_f32_e32 v240, v116, v240
	v_fma_f32 v97, v14, s9, v242
	v_mfma_f32_32x32x16_bf16 v[48:63], v[228:231], v[84:87], v[48:63]
	v_add_f32_e32 v241, v117, v241
	v_exp_f32_e32 v118, v118
	v_exp_f32_e32 v119, v119
	v_add_f32_e32 v240, v132, v240
	v_fma_f32 v98, v14, s96, v242
	v_mfma_f32_32x32x16_bf16 v[48:63], v[232:235], v[88:91], v[48:63]
	v_add_f32_e32 v241, v133, v241
	v_exp_f32_e32 v134, v134
	v_exp_f32_e32 v135, v135
	v_add_f32_e32 v240, v118, v240
	v_fma_f32 v99, v14, s97, v242
	v_mfma_f32_32x32x16_bf16 v[48:63], v[236:239], v[92:95], v[48:63]
	v_add_f32_e32 v241, v119, v241
	v_exp_f32_e32 v120, v120
	v_exp_f32_e32 v121, v121
	v_add_f32_e32 v240, v134, v240
	v_fma_f32 v100, v14, s94, v242
	ds_read_b128 v[224:227], v251 offset:23040
	ds_read_b128 v[228:231], v251 offset:23072
	ds_read_b128 v[232:235], v251 offset:23104
	ds_read_b128 v[236:239], v251 offset:23136
	s_waitcnt lgkmcnt(4)
	v_mfma_f32_32x32x16_bf16 v[32:47], v[160:163], v[80:83], v[32:47]
	v_add_f32_e32 v241, v135, v241
	v_exp_f32_e32 v136, v136
	v_exp_f32_e32 v137, v137
	v_add_f32_e32 v240, v120, v240
	v_fma_f32 v101, v14, s95, v242
	v_mfma_f32_32x32x16_bf16 v[32:47], v[164:167], v[84:87], v[32:47]
	v_add_f32_e32 v241, v121, v241
	v_exp_f32_e32 v122, v122
	v_exp_f32_e32 v123, v123
	v_add_f32_e32 v240, v136, v240
	v_fma_f32 v102, v14, s92, v242
	v_mfma_f32_32x32x16_bf16 v[32:47], v[168:171], v[88:91], v[32:47]
	v_add_f32_e32 v241, v137, v241
	v_exp_f32_e32 v138, v138
	v_exp_f32_e32 v139, v139
	v_add_f32_e32 v240, v122, v240
	v_fma_f32 v103, v14, s93, v242
	v_mfma_f32_32x32x16_bf16 v[32:47], v[172:175], v[92:95], v[32:47]
	v_add_f32_e32 v241, v123, v241
	v_exp_f32_e32 v124, v124
	v_exp_f32_e32 v125, v125
	v_add_f32_e32 v240, v138, v240
	v_fma_f32 v104, v14, s90, v242
	ds_read_b128 v[160:163], v245 offset:4608
	ds_read_b128 v[164:167], v245 offset:4640
	ds_read_b128 v[168:171], v245 offset:4672
	ds_read_b128 v[172:175], v245 offset:4704
	s_waitcnt lgkmcnt(4)
	v_mfma_f32_32x32x16_bf16 v[16:31], v[224:227], v[80:83], v[16:31]
	v_add_f32_e32 v241, v139, v241
	v_exp_f32_e32 v140, v140
	v_exp_f32_e32 v141, v141
	v_add_f32_e32 v240, v124, v240
	v_fma_f32 v105, v14, s91, v242
	v_mfma_f32_32x32x16_bf16 v[16:31], v[228:231], v[84:87], v[16:31]
	v_add_f32_e32 v241, v125, v241
	v_exp_f32_e32 v126, v126
	v_exp_f32_e32 v127, v127
	v_add_f32_e32 v240, v140, v240
	v_fma_f32 v106, v14, s88, v242
	v_mfma_f32_32x32x16_bf16 v[16:31], v[232:235], v[88:91], v[16:31]
	v_add_f32_e32 v241, v141, v241
	v_exp_f32_e32 v142, v142
	v_exp_f32_e32 v143, v143
	v_add_f32_e32 v240, v126, v240
	v_fma_f32 v107, v14, s89, v242
	v_mfma_f32_32x32x16_bf16 v[16:31], v[236:239], v[92:95], v[16:31]
	v_add_f32_e32 v241, v127, v241
	v_fma_f32 v108, v14, s86, v242
	v_fma_f32 v109, v14, s87, v242
	v_fma_f32 v110, v14, s78, v242
	v_fma_f32 v111, v14, s79, v242
	ds_read_b128 v[224:227], v245 offset:0
	ds_read_b128 v[228:231], v245 offset:32
	ds_read_b128 v[232:235], v245 offset:64
	ds_read_b128 v[236:239], v245 offset:96
	s_waitcnt lgkmcnt(4)
	v_mfma_f32_32x32x16_bf16 v[96:111], v[160:163], v[2:5], v[96:111]
	v_mov_b32_e32 v80, v242
	v_add_f32_e32 v81, v14, v242
	v_fma_f32 v82, v14, s62, v242
	v_fma_f32 v83, v14, s63, v242
	v_mfma_f32_32x32x16_bf16 v[96:111], v[164:167], v[6:9], v[96:111]
	v_fma_f32 v84, v14, s64, v242
	v_fma_f32 v85, v14, s65, v242
	v_fma_f32 v86, v14, s66, v242
	v_fma_f32 v87, v14, s67, v242
	v_mfma_f32_32x32x16_bf16 v[96:111], v[168:171], v[10:13], v[96:111]
	v_fma_f32 v88, v14, s68, v242
	v_fma_f32 v89, v14, s69, v242
	v_fma_f32 v90, v14, s70, v242
	v_fma_f32 v91, v14, s71, v242
	v_mfma_f32_32x32x16_bf16 v[96:111], v[172:175], v[144:147], v[96:111]
	v_fma_f32 v92, v14, s72, v242
	v_fma_f32 v93, v14, s73, v242
	v_fma_f32 v94, v14, s76, v242
	v_fma_f32 v95, v14, s77, v242
	ds_read_b128 v[160:163], v251 offset:36864
	ds_read_b128 v[164:167], v251 offset:36896
	ds_read_b128 v[168:171], v251 offset:36928
	ds_read_b128 v[172:175], v251 offset:36960
	s_waitcnt lgkmcnt(4)
	v_mfma_f32_32x32x16_bf16 v[80:95], v[224:227], v[2:5], v[80:95]
	s_nop 0
	v_add_f32_e32 v240, v142, v240
	v_add_f32_e32 v241, v143, v241
	v_cvt_pk_bf16_f32 v112, v112, v113
	v_cvt_pk_bf16_f32 v113, v114, v115
	v_cvt_pk_bf16_f32 v114, v116, v117
	v_mfma_f32_32x32x16_bf16 v[80:95], v[228:231], v[6:9], v[80:95]
	v_cvt_pk_bf16_f32 v115, v118, v119
	v_cvt_pk_bf16_f32 v116, v120, v121
	v_cvt_pk_bf16_f32 v117, v122, v123
	v_cvt_pk_bf16_f32 v118, v124, v125
	v_cvt_pk_bf16_f32 v119, v126, v127
	v_cvt_pk_bf16_f32 v120, v128, v129
	v_mfma_f32_32x32x16_bf16 v[80:95], v[232:235], v[10:13], v[80:95]
	v_cvt_pk_bf16_f32 v121, v130, v131
	v_cvt_pk_bf16_f32 v122, v132, v133
	v_cvt_pk_bf16_f32 v123, v134, v135
	v_cvt_pk_bf16_f32 v124, v136, v137
	v_cvt_pk_bf16_f32 v125, v138, v139
	v_cvt_pk_bf16_f32 v126, v140, v141
	v_mfma_f32_32x32x16_bf16 v[80:95], v[236:239], v[144:147], v[80:95]
	v_cvt_pk_bf16_f32 v127, v142, v143
	v_add_f32_e32 v199, v240, v241
	s_branch .Ld_tail1

; template <int DQK, int DV, int FLAGS, int qp, int kp, int vts, int op> ...
;     ...
;             if (more) ATT_GLOAD((FLAGS & AF_REV) ? t - 1 : t + 1);
.Ld_top2:
	s_cmp_le_i32 s23, s24
	s_cbranch_scc1 .Ld_gen2
	s_add_i32 s13, s23, 1
	s_cmp_ge_i32 s13, s3
	s_cbranch_scc1 .Ld_gen2
	ds_read_b128 v[224:227], v251 offset:41472
	ds_read_b128 v[228:231], v251 offset:41504
	ds_read_b128 v[232:235], v251 offset:41536
	ds_read_b128 v[236:239], v251 offset:41568
	v_mfma_f32_32x32x16_bf16 v[64:79], v[160:163], v[112:115], v[64:79]
	v_exp_f32_e32 v80, v80
	v_exp_f32_e32 v81, v81
	v_exp_f32_e32 v96, v96
	v_exp_f32_e32 v97, v97
	v_add_u32_e32 v246, 64, v205
	s_add_i32 s12, s23, 2
	s_cmp_ge_i32 s12, s3
	s_cbranch_scc1 .Ld_ng_s2
	s_ashr_i32 s35, s34, 31
	s_lshl_b64 s[6:7], s[34:35], 17
	s_add_u32 s6, s6, s100
	s_addc_u32 s7, s7, s101
	s_lshl_b64 s[10:11], s[34:35], 7
	s_add_u32 s10, s18, s10
	s_addc_u32 s11, s19, s11
	s_add_i32 m0, s98, 0x0
	s_nop 0
	global_load_lds_dwordx4 v148, s[6:7]
	s_cmp_eq_u32 s98, 0
	s_cselect_b64 s[12:13], s[6:7], s[10:11]
	s_add_i32 m0, s98, 0x2000
	s_nop 0
	global_load_lds_dwordx4 v149, s[12:13]
	s_add_i32 m0, s98, 0x4000
	s_nop 0
	global_load_lds_dwordx4 v150, s[10:11]
	s_cmp_lt_u32 s98, 0xc00
	s_cbranch_scc0 .Ld_no4_s2
	s_add_i32 m0, s98, 0x6000
	s_nop 0
	global_load_lds_dwordx4 v151, s[10:11]

.Ld_ng_s2:
	v_mfma_f32_32x32x16_bf16 v[64:79], v[164:167], v[116:119], v[64:79]
	v_add_f32_e32 v240, v80, v199
	v_exp_f32_e32 v82, v82
	v_exp_f32_e32 v83, v83
	v_add_f32_e32 v240, v96, v240
	v_cvt_f32_i32_e32 v246, v246
	v_mfma_f32_32x32x16_bf16 v[64:79], v[168:171], v[120:123], v[64:79]
	v_add_f32_e32 v241, v81, v97
	v_exp_f32_e32 v98, v98
	v_exp_f32_e32 v99, v99
	v_add_f32_e32 v240, v82, v240
	v_fma_f32 v242, -v14, v246, -v222
	v_mfma_f32_32x32x16_bf16 v[64:79], v[172:175], v[124:127], v[64:79]
	v_add_f32_e32 v241, v83, v241
	v_exp_f32_e32 v84, v84
	v_exp_f32_e32 v85, v85
	v_add_f32_e32 v240, v98, v240
	v_fma_f32 v128, v14, s8, v242
	ds_read_b128 v[160:163], v251 offset:46080
	ds_read_b128 v[164:167], v251 offset:46112
	ds_read_b128 v[168:171], v251 offset:46144
	ds_read_b128 v[172:175], v251 offset:46176
	s_waitcnt lgkmcnt(4)
	v_mfma_f32_32x32x16_bf16 v[48:63], v[224:227], v[112:115], v[48:63]
	v_add_f32_e32 v241, v99, v241
	v_exp_f32_e32 v100, v100
	v_exp_f32_e32 v101, v101
	v_add_f32_e32 v240, v84, v240
	v_fma_f32 v129, v14, s9, v242
	v_mfma_f32_32x32x16_bf16 v[48:63], v[228:231], v[116:119], v[48:63]
	v_add_f32_e32 v241, v85, v241
	v_exp_f32_e32 v86, v86
	v_exp_f32_e32 v87, v87
	v_add_f32_e32 v240, v100, v240
	v_fma_f32 v130, v14, s96, v242
	v_mfma_f32_32x32x16_bf16 v[48:63], v[232:235], v[120:123], v[48:63]
	v_add_f32_e32 v241, v101, v241
	v_exp_f32_e32 v102, v102
	v_exp_f32_e32 v103, v103
	v_add_f32_e32 v240, v86, v240
	v_fma_f32 v131, v14, s97, v242
	v_mfma_f32_32x32x16_bf16 v[48:63], v[236:239], v[124:127], v[48:63]
	v_add_f32_e32 v241, v87, v241
	v_exp_f32_e32 v88, v88
	v_exp_f32_e32 v89, v89
	v_add_f32_e32 v240, v102, v240
	v_fma_f32 v132, v14, s94, v242
	ds_read_b128 v[224:227], v251 offset:50688
	ds_read_b128 v[228:231], v251 offset:50720
	ds_read_b128 v[232:235], v251 offset:50752
	ds_read_b128 v[236:239], v251 offset:50784
	s_waitcnt lgkmcnt(4)
	v_mfma_f32_32x32x16_bf16 v[32:47], v[160:163], v[112:115], v[32:47]
	v_add_f32_e32 v241, v103, v241
	v_exp_f32_e32 v104, v104
	v_exp_f32_e32 v105, v105
	v_add_f32_e32 v240, v88, v240
	v_fma_f32 v133, v14, s95, v242
	v_mfma_f32_32x32x16_bf16 v[32:47], v[164:167], v[116:119], v[32:47]
	v_add_f32_e32 v241, v89, v241
	v_exp_f32_e32 v90, v90
	v_exp_f32_e32 v91, v91
	v_add_f32_e32 v240, v104, v240
	v_fma_f32 v134, v14, s92, v242
	v_mfma_f32_32x32x16_bf16 v[32:47], v[168:171], v[120:123], v[32:47]
	v_add_f32_e32 v241, v105, v241
	v_exp_f32_e32 v106, v106
	v_exp_f32_e32 v107, v107
	v_add_f32_e32 v240, v90, v240
	v_fma_f32 v135, v14, s93, v242
	v_mfma_f32_32x32x16_bf16 v[32:47], v[172:175], v[124:127], v[32:47]
	v_add_f32_e32 v241, v91, v241
	v_exp_f32_e32 v92, v92
	v_exp_f32_e32 v93, v93
	v_add_f32_e32 v240, v106, v240
	v_fma_f32 v136, v14, s90, v242
	ds_read_b128 v[160:163], v245 offset:32256
	ds_read_b128 v[164:167], v245 offset:32288
	ds_read_b128 v[168:171], v245 offset:32320
	ds_read_b128 v[172:175], v245 offset:32352
	s_waitcnt lgkmcnt(4)
	v_mfma_f32_32x32x16_bf16 v[16:31], v[224:227], v[112:115], v[16:31]
	v_add_f32_e32 v241, v107, v241
	v_exp_f32_e32 v108, v108
	v_exp_f32_e32 v109, v109
	v_add_f32_e32 v240, v92, v240
	v_fma_f32 v137, v14, s91, v242
	v_mfma_f32_32x32x16_bf16 v[16:31], v[228:231], v[116:119], v[16:31]
	v_add_f32_e32 v241, v93, v241
	v_exp_f32_e32 v94, v94
	v_exp_f32_e32 v95, v95
	v_add_f32_e32 v240, v108, v240
	v_fma_f32 v138, v14, s88, v242
	v_mfma_f32_32x32x16_bf16 v[16:31], v[232:235], v[120:123], v[16:31]
	v_add_f32_e32 v241, v109, v241
	v_exp_f32_e32 v110, v110
	v_exp_f32_e32 v111, v111
	v_add_f32_e32 v240, v94, v240
	v_fma_f32 v139, v14, s89, v242
	v_mfma_f32_32x32x16_bf16 v[16:31], v[236:239], v[124:127], v[16:31]
	v_add_f32_e32 v241, v95, v241
	v_fma_f32 v140, v14, s86, v242
	v_fma_f32 v141, v14, s87, v242
	v_fma_f32 v142, v14, s78, v242
	v_fma_f32 v143, v14, s79, v242
	ds_read_b128 v[224:227], v245 offset:27648
	ds_read_b128 v[228:231], v245 offset:27680
	ds_read_b128 v[232:235], v245 offset:27712
	ds_read_b128 v[236:239], v245 offset:27744
	s_waitcnt lgkmcnt(4)
	v_mfma_f32_32x32x16_bf16 v[128:143], v[160:163], v[2:5], v[128:143]
	v_mov_b32_e32 v112, v242
	v_add_f32_e32 v113, v14, v242
	v_fma_f32 v114, v14, s62, v242
	v_fma_f32 v115, v14, s63, v242
	v_mfma_f32_32x32x16_bf16 v[128:143], v[164:167], v[6:9], v[128:143]
	v_fma_f32 v116, v14, s64, v242
	v_fma_f32 v117, v14, s65, v242
	v_fma_f32 v118, v14, s66, v242
	v_fma_f32 v119, v14, s67, v242
	v_mfma_f32_32x32x16_bf16 v[128:143], v[168:171], v[10:13], v[128:143]
	v_fma_f32 v120, v14, s68, v242
	v_fma_f32 v121, v14, s69, v242
	v_fma_f32 v122, v14, s70, v242
	v_fma_f32 v123, v14, s71, v242
	v_mfma_f32_32x32x16_bf16 v[128:143], v[172:175], v[144:147], v[128:143]
	v_fma_f32 v124, v14, s72, v242
	v_fma_f32 v125, v14, s73, v242
	v_fma_f32 v126, v14, s76, v242
	v_fma_f32 v127, v14, s77, v242
	ds_read_b128 v[160:163], v250 offset:9216
	ds_read_b128 v[164:167], v250 offset:9248
	ds_read_b128 v[168:171], v250 offset:9280
	ds_read_b128 v[172:175], v250 offset:9312
	s_waitcnt lgkmcnt(4)
	v_mfma_f32_32x32x16_bf16 v[112:127], v[224:227], v[2:5], v[112:127]
	s_nop 0
	v_add_f32_e32 v240, v110, v240
	v_add_f32_e32 v241, v111, v241
	v_cvt_pk_bf16_f32 v80, v80, v81
	v_cvt_pk_bf16_f32 v81, v82, v83
	v_cvt_pk_bf16_f32 v82, v84, v85
	v_mfma_f32_32x32x16_bf16 v[112:127], v[228:231], v[6:9], v[112:127]
	v_cvt_pk_bf16_f32 v83, v86, v87
	v_cvt_pk_bf16_f32 v84, v88, v89
	v_cvt_pk_bf16_f32 v85, v90, v91
	v_cvt_pk_bf16_f32 v86, v92, v93
	v_cvt_pk_bf16_f32 v87, v94, v95
	v_cvt_pk_bf16_f32 v88, v96, v97
	v_mfma_f32_32x32x16_bf16 v[112:127], v[232:235], v[10:13], v[112:127]
	v_cvt_pk_bf16_f32 v89, v98, v99
	v_cvt_pk_bf16_f32 v90, v100, v101
	v_cvt_pk_bf16_f32 v91, v102, v103
	v_cvt_pk_bf16_f32 v92, v104, v105
	v_cvt_pk_bf16_f32 v93, v106, v107
	v_cvt_pk_bf16_f32 v94, v108, v109
	v_mfma_f32_32x32x16_bf16 v[112:127], v[236:239], v[144:147], v[112:127]
	v_cvt_pk_bf16_f32 v95, v110, v111
	v_add_f32_e32 v199, v240, v241
	s_branch .Ld_tail2

; template <int DQK, int DV, int FLAGS, int qp, int kp, int vts, int op> ...
;     ...
;             if (more) ATT_GLOAD((FLAGS & AF_REV) ? t - 1 : t + 1);
.Ld_top3:
	s_cmp_le_i32 s23, s24
	s_cbranch_scc1 .Ld_gen3
	s_add_i32 s13, s23, 1
	s_cmp_ge_i32 s13, s3
	s_cbranch_scc1 .Ld_gen3
	ds_read_b128 v[224:227], v250 offset:13824
	ds_read_b128 v[228:231], v250 offset:13856
	ds_read_b128 v[232:235], v250 offset:13888
	ds_read_b128 v[236:239], v250 offset:13920
	v_mfma_f32_32x32x16_bf16 v[64:79], v[160:163], v[80:83], v[64:79]
	v_exp_f32_e32 v112, v112
	v_exp_f32_e32 v113, v113
	v_exp_f32_e32 v128, v128
	v_exp_f32_e32 v129, v129
	v_add_u32_e32 v246, 64, v205
	s_add_i32 s12, s23, 2
	s_cmp_ge_i32 s12, s3
	s_cbranch_scc1 .Ld_ng_s3
	s_ashr_i32 s35, s34, 31
	s_lshl_b64 s[6:7], s[34:35], 17
	s_add_u32 s6, s6, s100
	s_addc_u32 s7, s7, s101
	s_lshl_b64 s[10:11], s[34:35], 7
	s_add_u32 s10, s18, s10
	s_addc_u32 s11, s19, s11
	s_add_i32 m0, s98, 0x6c00
	s_nop 0
	global_load_lds_dwordx4 v148, s[6:7]
	s_cmp_eq_u32 s98, 0
	s_cselect_b64 s[12:13], s[6:7], s[10:11]
	s_add_i32 m0, s98, 0x8c00
	s_nop 0
	global_load_lds_dwordx4 v149, s[12:13]
	s_add_i32 m0, s98, 0xac00
	s_nop 0
	global_load_lds_dwordx4 v150, s[10:11]
	s_cmp_lt_u32 s98, 0xc00
	s_cbranch_scc0 .Ld_no4_s3
	s_add_i32 m0, s98, 0xcc00
	s_nop 0
	global_load_lds_dwordx4 v151, s[10:11]

.Ld_ng_s3:
	v_mfma_f32_32x32x16_bf16 v[64:79], v[164:167], v[84:87], v[64:79]
	v_add_f32_e32 v240, v112, v199
	v_exp_f32_e32 v114, v114
	v_exp_f32_e32 v115, v115
	v_add_f32_e32 v240, v128, v240
	v_cvt_f32_i32_e32 v246, v246
	v_mfma_f32_32x32x16_bf16 v[64:79], v[168:171], v[88:91], v[64:79]
	v_add_f32_e32 v241, v113, v129
	v_exp_f32_e32 v130, v130
	v_exp_f32_e32 v131, v131
	v_add_f32_e32 v240, v114, v240
	v_fma_f32 v242, -v14, v246, -v222
	v_mfma_f32_32x32x16_bf16 v[64:79], v[172:175], v[92:95], v[64:79]
	v_add_f32_e32 v241, v115, v241
	v_exp_f32_e32 v116, v116
	v_exp_f32_e32 v117, v117
	v_add_f32_e32 v240, v130, v240
	v_fma_f32 v96, v14, s8, v242
	ds_read_b128 v[160:163], v250 offset:18432
	ds_read_b128 v[164:167], v250 offset:18464
	ds_read_b128 v[168:171], v250 offset:18496
	ds_read_b128 v[172:175], v250 offset:18528
	s_waitcnt lgkmcnt(4)
	v_mfma_f32_32x32x16_bf16 v[48:63], v[224:227], v[80:83], v[48:63]
	v_add_f32_e32 v241, v131, v241
	v_exp_f32_e32 v132, v132
	v_exp_f32_e32 v133, v133
	v_add_f32_e32 v240, v116, v240
	v_fma_f32 v97, v14, s9, v242
	v_mfma_f32_32x32x16_bf16 v[48:63], v[228:231], v[84:87], v[48:63]
	v_add_f32_e32 v241, v117, v241
	v_exp_f32_e32 v118, v118
	v_exp_f32_e32 v119, v119
	v_add_f32_e32 v240, v132, v240
	v_fma_f32 v98, v14, s96, v242
	v_mfma_f32_32x32x16_bf16 v[48:63], v[232:235], v[88:91], v[48:63]
	v_add_f32_e32 v241, v133, v241
	v_exp_f32_e32 v134, v134
	v_exp_f32_e32 v135, v135
	v_add_f32_e32 v240, v118, v240
	v_fma_f32 v99, v14, s97, v242
	v_mfma_f32_32x32x16_bf16 v[48:63], v[236:239], v[92:95], v[48:63]
	v_add_f32_e32 v241, v119, v241
	v_exp_f32_e32 v120, v120
	v_exp_f32_e32 v121, v121
	v_add_f32_e32 v240, v134, v240
	v_fma_f32 v100, v14, s94, v242
	ds_read_b128 v[224:227], v250 offset:23040
	ds_read_b128 v[228:231], v250 offset:23072
	ds_read_b128 v[232:235], v250 offset:23104
	ds_read_b128 v[236:239], v250 offset:23136
	s_waitcnt lgkmcnt(4)
	v_mfma_f32_32x32x16_bf16 v[32:47], v[160:163], v[80:83], v[32:47]
	v_add_f32_e32 v241, v135, v241
	v_exp_f32_e32 v136, v136
	v_exp_f32_e32 v137, v137
	v_add_f32_e32 v240, v120, v240
	v_fma_f32 v101, v14, s95, v242
	v_mfma_f32_32x32x16_bf16 v[32:47], v[164:167], v[84:87], v[32:47]
	v_add_f32_e32 v241, v121, v241
	v_exp_f32_e32 v122, v122
	v_exp_f32_e32 v123, v123
	v_add_f32_e32 v240, v136, v240
	v_fma_f32 v102, v14, s92, v242
	v_mfma_f32_32x32x16_bf16 v[32:47], v[168:171], v[88:91], v[32:47]
	v_add_f32_e32 v241, v137, v241
	v_exp_f32_e32 v138, v138
	v_exp_f32_e32 v139, v139
	v_add_f32_e32 v240, v122, v240
	v_fma_f32 v103, v14, s93, v242
	v_mfma_f32_32x32x16_bf16 v[32:47], v[172:175], v[92:95], v[32:47]
	v_add_f32_e32 v241, v123, v241
	v_exp_f32_e32 v124, v124
	v_exp_f32_e32 v125, v125
	v_add_f32_e32 v240, v138, v240
	v_fma_f32 v104, v14, s90, v242
	ds_read_b128 v[160:163], v244 offset:4608
	ds_read_b128 v[164:167], v244 offset:4640
	ds_read_b128 v[168:171], v244 offset:4672
	ds_read_b128 v[172:175], v244 offset:4704
	s_waitcnt lgkmcnt(4)
	v_mfma_f32_32x32x16_bf16 v[16:31], v[224:227], v[80:83], v[16:31]
	v_add_f32_e32 v241, v139, v241
	v_exp_f32_e32 v140, v140
	v_exp_f32_e32 v141, v141
	v_add_f32_e32 v240, v124, v240
	v_fma_f32 v105, v14, s91, v242
	v_mfma_f32_32x32x16_bf16 v[16:31], v[228:231], v[84:87], v[16:31]
	v_add_f32_e32 v241, v125, v241
	v_exp_f32_e32 v126, v126
	v_exp_f32_e32 v127, v127
	v_add_f32_e32 v240, v140, v240
	v_fma_f32 v106, v14, s88, v242
	v_mfma_f32_32x32x16_bf16 v[16:31], v[232:235], v[88:91], v[16:31]
	v_add_f32_e32 v241, v141, v241
	v_exp_f32_e32 v142, v142
	v_exp_f32_e32 v143, v143
	v_add_f32_e32 v240, v126, v240
	v_fma_f32 v107, v14, s89, v242
	v_mfma_f32_32x32x16_bf16 v[16:31], v[236:239], v[92:95], v[16:31]
	v_add_f32_e32 v241, v127, v241
	v_fma_f32 v108, v14, s86, v242
	v_fma_f32 v109, v14, s87, v242
	v_fma_f32 v110, v14, s78, v242
	v_fma_f32 v111, v14, s79, v242
	ds_read_b128 v[224:227], v244 offset:0
	ds_read_b128 v[228:231], v244 offset:32
	ds_read_b128 v[232:235], v244 offset:64
	ds_read_b128 v[236:239], v244 offset:96
	s_waitcnt lgkmcnt(4)
	v_mfma_f32_32x32x16_bf16 v[96:111], v[160:163], v[2:5], v[96:111]
	v_mov_b32_e32 v80, v242
	v_add_f32_e32 v81, v14, v242
	v_fma_f32 v82, v14, s62, v242
	v_fma_f32 v83, v14, s63, v242
	v_mfma_f32_32x32x16_bf16 v[96:111], v[164:167], v[6:9], v[96:111]
	v_fma_f32 v84, v14, s64, v242
	v_fma_f32 v85, v14, s65, v242
	v_fma_f32 v86, v14, s66, v242
	v_fma_f32 v87, v14, s67, v242
	v_mfma_f32_32x32x16_bf16 v[96:111], v[168:171], v[10:13], v[96:111]
	v_fma_f32 v88, v14, s68, v242
	v_fma_f32 v89, v14, s69, v242
	v_fma_f32 v90, v14, s70, v242
	v_fma_f32 v91, v14, s71, v242
	v_mfma_f32_32x32x16_bf16 v[96:111], v[172:175], v[144:147], v[96:111]
	v_fma_f32 v92, v14, s72, v242
	v_fma_f32 v93, v14, s73, v242
	v_fma_f32 v94, v14, s76, v242
	v_fma_f32 v95, v14, s77, v242
	ds_read_b128 v[160:163], v250 offset:36864
	ds_read_b128 v[164:167], v250 offset:36896
	ds_read_b128 v[168:171], v250 offset:36928
	ds_read_b128 v[172:175], v250 offset:36960
	s_waitcnt lgkmcnt(4)
	v_mfma_f32_32x32x16_bf16 v[80:95], v[224:227], v[2:5], v[80:95]
	s_nop 0
	v_add_f32_e32 v240, v142, v240
	v_add_f32_e32 v241, v143, v241
	v_cvt_pk_bf16_f32 v112, v112, v113
	v_cvt_pk_bf16_f32 v113, v114, v115
	v_cvt_pk_bf16_f32 v114, v116, v117
	v_mfma_f32_32x32x16_bf16 v[80:95], v[228:231], v[6:9], v[80:95]
	v_cvt_pk_bf16_f32 v115, v118, v119
	v_cvt_pk_bf16_f32 v116, v120, v121
	v_cvt_pk_bf16_f32 v117, v122, v123
	v_cvt_pk_bf16_f32 v118, v124, v125
	v_cvt_pk_bf16_f32 v119, v126, v127
	v_cvt_pk_bf16_f32 v120, v128, v129
	v_mfma_f32_32x32x16_bf16 v[80:95], v[232:235], v[10:13], v[80:95]
	v_cvt_pk_bf16_f32 v121, v130, v131
	v_cvt_pk_bf16_f32 v122, v132, v133
	v_cvt_pk_bf16_f32 v123, v134, v135
	v_cvt_pk_bf16_f32 v124, v136, v137
	v_cvt_pk_bf16_f32 v125, v138, v139
	v_cvt_pk_bf16_f32 v126, v140, v141
	v_mfma_f32_32x32x16_bf16 v[80:95], v[236:239], v[144:147], v[80:95]
	v_cvt_pk_bf16_f32 v127, v142, v143
	v_add_f32_e32 v199, v240, v241
	s_branch .Ld_tail3

; #define LAS __attribute__((address_space(3)))
; #define ATT_LSTORE(buf) do { LAS unsigned char* b_ = lds + (buf) * BUF; \
;         _Pragma("unroll") for (int i = 0; i < KPT; ++i) { if (KCH % NTHREADS == 0 || tid + i * NTHREADS < KCH) *(LAS u32x4*)(b_ + klo[i]) = kreg[i]; } \
;         _Pragma("unroll") for (int i = 0; i < VPT; ++i) *(LAS u32x4*)(b_ + vlo[i]) = vreg[i]; } while (0)
; template <int DQK, int DV, int FLAGS, int qp, int kp, int vts, int op> ...
;     ...
;             for (int d = 0; d < NDB; ++d) {
;                 if (d + 1 < NDB) {
; #pragma unroll
;                     for (int ks = 0; ks < 4; ++ks) vf[(d + 1) & 1][ks] = *(const LAS bf16x8*)(vb + (d + 1) * 32 * VROW + ks * 32);
;                 }
; #pragma unroll
;                 for (int ks = 0; ks < 4; ++ks) o[d] = __builtin_amdgcn_mfma_f32_32x32x16_bf16(vf[d & 1][ks], pf[ks], o[d], 0, 0, 0);
;                 __builtin_amdgcn_sched_barrier(0);
;             }
;     ...
;         if (skip && more) ATT_GLOAD((FLAGS & AF_REV) ? t - 1 : t + 1);
;         if (more) ATT_LSTORE(cur ^ 1);
;         __syncthreads();
;     }
.Ld_nopre_q3:
.Ld_tail3:
	s_waitcnt vmcnt(0)
	v_add_u32_e32 v205, 64, v205
	s_add_i32 s23, s23, 1
	s_cmp_ge_i32 s23, s3
	s_cbranch_scc1 .Ld_flush0
	s_waitcnt lgkmcnt(0)
	s_barrier
	s_branch .Ld_top0
.Ld_flush0:
	s_waitcnt vmcnt(0)
	s_waitcnt lgkmcnt(0)
	s_add_i32 s12, s23, -1
	s_and_b32 s12, s12, 3
	s_mulk_i32 s12, 0x6c00
	v_add3_u32 v246, s12, v203, v194
	ds_read_b128 v[224:227], v246 offset:13824
	ds_read_b128 v[228:231], v246 offset:13856
	ds_read_b128 v[232:235], v246 offset:13888
	ds_read_b128 v[236:239], v246 offset:13920
	v_mfma_f32_32x32x16_bf16 v[64:79], v[160:163], v[112:115], v[64:79]
	v_mfma_f32_32x32x16_bf16 v[64:79], v[164:167], v[116:119], v[64:79]
	v_mfma_f32_32x32x16_bf16 v[64:79], v[168:171], v[120:123], v[64:79]
	v_mfma_f32_32x32x16_bf16 v[64:79], v[172:175], v[124:127], v[64:79]
	ds_read_b128 v[160:163], v246 offset:18432
	ds_read_b128 v[164:167], v246 offset:18464
	ds_read_b128 v[168:171], v246 offset:18496
	ds_read_b128 v[172:175], v246 offset:18528
	s_waitcnt lgkmcnt(4)
	v_mfma_f32_32x32x16_bf16 v[48:63], v[224:227], v[112:115], v[48:63]
	v_mfma_f32_32x32x16_bf16 v[48:63], v[228:231], v[116:119], v[48:63]
	v_mfma_f32_32x32x16_bf16 v[48:63], v[232:235], v[120:123], v[48:63]
	v_mfma_f32_32x32x16_bf16 v[48:63], v[236:239], v[124:127], v[48:63]
	ds_read_b128 v[224:227], v246 offset:23040
	ds_read_b128 v[228:231], v246 offset:23072
	ds_read_b128 v[232:235], v246 offset:23104
	ds_read_b128 v[236:239], v246 offset:23136
	s_waitcnt lgkmcnt(4)
	v_mfma_f32_32x32x16_bf16 v[32:47], v[160:163], v[112:115], v[32:47]
	v_mfma_f32_32x32x16_bf16 v[32:47], v[164:167], v[116:119], v[32:47]
	v_mfma_f32_32x32x16_bf16 v[32:47], v[168:171], v[120:123], v[32:47]
	v_mfma_f32_32x32x16_bf16 v[32:47], v[172:175], v[124:127], v[32:47]
	s_waitcnt lgkmcnt(0)
	v_mfma_f32_32x32x16_bf16 v[16:31], v[224:227], v[112:115], v[16:31]
	v_mfma_f32_32x32x16_bf16 v[16:31], v[228:231], v[116:119], v[16:31]
	v_mfma_f32_32x32x16_bf16 v[16:31], v[232:235], v[120:123], v[16:31]
	v_mfma_f32_32x32x16_bf16 v[16:31], v[236:239], v[124:127], v[16:31]
	s_branch .LBB0_957
.Ld_flush1:
	s_waitcnt vmcnt(0)
	s_waitcnt lgkmcnt(0)
	s_add_i32 s12, s23, -1
	s_and_b32 s12, s12, 3
	s_mulk_i32 s12, 0x6c00
	v_add3_u32 v246, s12, v203, v194
	ds_read_b128 v[224:227], v246 offset:13824
	ds_read_b128 v[228:231], v246 offset:13856
	ds_read_b128 v[232:235], v246 offset:13888
	ds_read_b128 v[236:239], v246 offset:13920
	v_mfma_f32_32x32x16_bf16 v[64:79], v[160:163], v[80:83], v[64:79]
	v_mfma_f32_32x32x16_bf16 v[64:79], v[164:167], v[84:87], v[64:79]
	v_mfma_f32_32x32x16_bf16 v[64:79], v[168:171], v[88:91], v[64:79]
	v_mfma_f32_32x32x16_bf16 v[64:79], v[172:175], v[92:95], v[64:79]
	ds_read_b128 v[160:163], v246 offset:18432
	ds_read_b128 v[164:167], v246 offset:18464
	ds_read_b128 v[168:171], v246 offset:18496
	ds_read_b128 v[172:175], v246 offset:18528
	s_waitcnt lgkmcnt(4)
	v_mfma_f32_32x32x16_bf16 v[48:63], v[224:227], v[80:83], v[48:63]
	v_mfma_f32_32x32x16_bf16 v[48:63], v[228:231], v[84:87], v[48:63]
	v_mfma_f32_32x32x16_bf16 v[48:63], v[232:235], v[88:91], v[48:63]
	v_mfma_f32_32x32x16_bf16 v[48:63], v[236:239], v[92:95], v[48:63]
	ds_read_b128 v[224:227], v246 offset:23040
	ds_read_b128 v[228:231], v246 offset:23072
	ds_read_b128 v[232:235], v246 offset:23104
	ds_read_b128 v[236:239], v246 offset:23136
	s_waitcnt lgkmcnt(4)
	v_mfma_f32_32x32x16_bf16 v[32:47], v[160:163], v[80:83], v[32:47]
	v_mfma_f32_32x32x16_bf16 v[32:47], v[164:167], v[84:87], v[32:47]
	v_mfma_f32_32x32x16_bf16 v[32:47], v[168:171], v[88:91], v[32:47]
	v_mfma_f32_32x32x16_bf16 v[32:47], v[172:175], v[92:95], v[32:47]
	s_waitcnt lgkmcnt(0)
	v_mfma_f32_32x32x16_bf16 v[16:31], v[224:227], v[80:83], v[16:31]
	v_mfma_f32_32x32x16_bf16 v[16:31], v[228:231], v[84:87], v[16:31]
	v_mfma_f32_32x32x16_bf16 v[16:31], v[232:235], v[88:91], v[16:31]
	v_mfma_f32_32x32x16_bf16 v[16:31], v[236:239], v[92:95], v[16:31]
	s_branch .LBB0_957
